# baseline (speedup 1.0000x reference)
.LBB0_181:
	s_or_b64 exec, exec, s[0:1]
	v_mov_b32_e32 v150, v218
	s_and_b32 s99, s70, 3
	s_lshl_b32 s99, s99, 8
	s_add_i32 s99, s99, s70
	s_cmpk_gt_i32 s99, 0x2ff
	v_readfirstlane_b32 s2, v150
	s_cbranch_scc0 .LBB0_184
	s_cmpk_gt_u32 s99, 0x3ff
	s_mov_b64 s[6:7], 0
	s_cbranch_scc1 .LBB0_185
	s_lshr_b32 s1, s99, 3
	s_lshl_b32 s0, s99, 5
	s_and_b32 s1, s1, 28
	s_or_b32 s0, s1, s0
	s_bfe_u32 s24, s99, 0x20003
	s_bfe_u32 s85, s0, 0x60002
	s_lshl_b32 s0, s24, 20
	s_add_u32 s0, s36, s0
	s_addc_u32 s1, s37, 0
	s_lshl_b32 s3, s85, 20
	s_add_u32 s54, s94, s3
	s_addc_u32 s55, s95, 0
	s_mov_b32 s3, 1
	s_mov_b64 s[4:5], -1
	s_branch .LBB0_187

.LBB0_186:
.LBB0_187:
	v_writelane_b32 v252, s8, 22
	s_andn2_b64 vcc, exec, s[6:7]
	s_nop 0
	v_writelane_b32 v252, s9, 23
	v_writelane_b32 v252, s46, 24
	s_nop 1
	v_writelane_b32 v252, s47, 25
	v_writelane_b32 v252, s44, 26
	s_nop 1
	v_writelane_b32 v252, s45, 27
	v_writelane_b32 v252, s42, 28
	v_writelane_b32 v252, s40, 29
	s_nop 1
	v_writelane_b32 v252, s41, 30
	s_cbranch_vccnz .LBB0_189
	s_ashr_i32 s0, s99, 31
	s_lshr_b32 s0, s0, 29
	s_add_i32 s0, s99, s0
	s_and_b32 s1, s0, -8
	s_sub_i32 s1, s99, s1
	s_cmp_lt_i32 s1, 0
	s_movk_i32 s4, 0x61
	s_cselect_b32 s4, s4, 0x60
	s_mul_i32 s1, s4, s1
	s_ashr_i32 s0, s0, 3
	s_add_i32 s1, s1, s0
	s_mul_hi_i32 s0, s1, 0x2aaaaaab
	s_lshr_b32 s4, s0, 31
	s_ashr_i32 s0, s0, 4
	s_add_i32 s0, s0, s4
	s_lshl_b32 s5, s0, 3
	s_mulk_i32 s0, 0x60
	s_sub_i32 s0, s1, s0
	s_bfe_i32 s1, s0, 0x80000
	s_bfe_u32 s1, s1, 0x3000c
	s_add_i32 s1, s0, s1
	s_bfe_i32 s4, s1, 0x80000
	s_and_b32 s1, s1, 0xf8
	s_sub_i32 s0, s0, s1
	s_sext_i32_i8 s0, s0
	s_add_i32 s24, s5, s0
	s_sext_i32_i16 s6, s4
	s_ashr_i32 s25, s24, 31
	s_lshr_b32 s4, s6, 3
	s_ashr_i32 s85, s6, 3
	s_lshl_b64 s[0:1], s[24:25], 20
	s_add_u32 s0, s94, s0
	s_addc_u32 s1, s95, s1
	s_bfe_i64 s[4:5], s[4:5], 0x100000
	s_lshl_b64 s[4:5], s[4:5], 20
	s_add_u32 s54, s34, s4
	s_mov_b32 s3, 0
	s_addc_u32 s55, s35, s5
	s_mov_b64 s[4:5], -1

.LBB0_195:
	s_add_i32 s51, s51, 1
	s_and_b32 s98, s70, 3
	s_add_i32 s98, s98, s51
	s_and_b32 s98, s98, 3
	s_mul_i32 s2, s98, s62
	s_add_i32 s2, s2, s70
	s_movk_i32 s98, 0x7ff
	s_cmp_gt_u32 s51, 3
	s_cselect_b32 s2, s98, s2
	s_cmpk_gt_i32 s2, 0x2ff
	s_mov_b64 s[66:67], -1
	s_cbranch_scc0 .LBB0_198
	s_mov_b64 s[66:67], 0
	s_cmpk_gt_u32 s2, 0x3ff
	s_mov_b64 s[44:45], 0
	s_cbranch_scc1 .LBB0_198
	s_lshr_b32 s27, s2, 3
	s_lshl_b32 s26, s2, 5
	s_and_b32 s27, s27, 28
	s_or_b32 s27, s27, s26
	s_bfe_u32 s26, s2, 0x20003
	s_bfe_u32 s87, s27, 0x60002
	s_lshl_b32 s27, s26, 20
	s_add_u32 s38, s36, s27
	s_addc_u32 s39, s37, 0
	s_lshl_b32 s27, s87, 20
	s_add_u32 s42, s94, s27
	s_addc_u32 s43, s95, 0
	s_mov_b32 s86, 1
	s_mov_b64 s[44:45], -1
